# baseline (speedup 1.0000x reference)
.LBB0_115:
	v_ashrrev_i32_e32 v108, 2, v65
	v_bfi_b32 v95, -16, v108, v65
	v_lshrrev_b32_e32 v2, 1, v65
	v_ashrrev_i32_e32 v64, 4, v65
	v_mad_i64_i32 v[0:1], s[2:3], s0, v95, 0
	v_and_b32_e32 v66, 24, v2
	v_add_u32_e32 v34, s70, v64
	v_and_b32_e32 v101, 15, v65
	v_lshl_add_u64 v[0:1], v[0:1], 1, s[34:35]
	v_lshlrev_b32_e32 v128, 1, v66
	s_waitcnt vmcnt(4)
	v_mad_i64_i32 v[16:17], s[2:3], s4, v34, 0
	v_lshl_add_u64 v[12:13], v[0:1], 0, v[128:129]
	v_lshl_add_u64 v[16:17], v[16:17], 1, s[40:41]
	v_lshlrev_b32_e32 v128, 4, v101
	v_lshl_add_u64 v[20:21], v[16:17], 0, v[128:129]
	v_mad_i64_i32 v[16:17], s[2:3], s92, v108, 0
	v_and_b32_e32 v67, 3, v65
	v_lshl_add_u64 v[16:17], v[16:17], 1, s[62:63]
	s_ashr_i32 s71, s70, 31
	v_lshl_add_u64 v[16:17], s[70:71], 1, v[16:17]
	v_lshlrev_b32_e32 v32, 4, v67
	v_mov_b32_e32 v33, v129
	s_lshl_b32 s66, s4, 6
	global_load_dwordx4 v[0:3], v[12:13], off
	global_load_dwordx4 v[4:7], v[12:13], off offset:64
	global_load_dwordx4 v[8:11], v[12:13], off offset:128
	s_nop 0
	global_load_dwordx4 v[12:15], v[12:13], off offset:192
	v_lshl_add_u64 v[28:29], v[16:17], 0, v[32:33]
	global_load_dwordx4 v[16:19], v[20:21], off
	v_lshl_add_u64 v[20:21], v[20:21], 0, s[66:67]
	global_load_dwordx4 v[20:23], v[20:21], off
	s_nop 0
	global_load_dwordx4 v[24:27], v[28:29], off
	s_nop 0
	global_load_dwordx4 v[28:31], v[28:29], off offset:64
	v_and_b32_e32 v33, 63, v65
	v_lshlrev_b32_e32 v33, 2, v33
	v_mov_b32_e32 v126, -1
	s_andn2_b64 vcc, exec, s[60:61]
	v_xor_b32_e32 v97, 64, v33
	v_xor_b32_e32 v99, 0x80, v33
	s_cbranch_vccnz .LBB0_133
	s_lshl_b32 s0, s47, 5
	s_lshl_b32 s1, s1, 3
	s_add_i32 s0, s1, s0
	s_ashr_i32 s1, s0, 31
	s_lshl_b64 s[0:1], s[0:1], 9
	v_readlane_b32 s2, v254, 33
	s_add_u32 s0, s2, s0
	v_readlane_b32 s2, v254, 34
	s_addc_u32 s1, s2, s1
	v_lshlrev_b32_e32 v36, 2, v66
	v_mov_b32_e32 v37, v129
	s_cmpk_gt_u32 s45, 0xff
	v_lshl_add_u64 v[52:53], s[0:1], 0, v[36:37]
	v_xor_b32_e32 v69, 64, v33
	v_xor_b32_e32 v35, 0x80, v33
	v_mov_b32_e32 v76, 0xf149f2ca
	s_cselect_b64 s[94:95], -1, 0
	s_cmpk_lt_u32 s45, 0x100
	s_waitcnt vmcnt(6)
	v_lshlrev_b32_e32 v63, 16, v4
	v_lshlrev_b32_e32 v62, 16, v0
	v_and_b32_e32 v75, 0xffff0000, v4
	v_and_b32_e32 v74, 0xffff0000, v0
	v_lshlrev_b32_e32 v73, 16, v5
	v_lshlrev_b32_e32 v72, 16, v1
	v_and_b32_e32 v71, 0xffff0000, v5
	v_and_b32_e32 v70, 0xffff0000, v1
	v_lshlrev_b32_e32 v61, 16, v6
	v_lshlrev_b32_e32 v60, 16, v2
	v_and_b32_e32 v59, 0xffff0000, v6
	v_and_b32_e32 v58, 0xffff0000, v2
	v_lshlrev_b32_e32 v57, 16, v7
	v_lshlrev_b32_e32 v56, 16, v3
	v_and_b32_e32 v55, 0xffff0000, v7
	v_and_b32_e32 v54, 0xffff0000, v3
	s_waitcnt vmcnt(4)
	v_lshlrev_b32_e32 v49, 16, v12
	v_lshlrev_b32_e32 v48, 16, v8
	v_and_b32_e32 v51, 0xffff0000, v12
	v_and_b32_e32 v50, 0xffff0000, v8
	v_lshlrev_b32_e32 v47, 16, v13
	v_lshlrev_b32_e32 v46, 16, v9
	v_and_b32_e32 v45, 0xffff0000, v13
	v_and_b32_e32 v44, 0xffff0000, v9
	v_lshlrev_b32_e32 v43, 16, v14
	v_lshlrev_b32_e32 v42, 16, v10
	v_and_b32_e32 v41, 0xffff0000, v14
	v_and_b32_e32 v40, 0xffff0000, v10
	v_lshlrev_b32_e32 v39, 16, v15
	v_lshlrev_b32_e32 v38, 16, v11
	v_and_b32_e32 v37, 0xffff0000, v15
	v_and_b32_e32 v36, 0xffff0000, v11
	v_mov_b32_e32 v77, 0xf149f2ca
	s_cbranch_scc1 .LBB0_118
	global_load_dwordx4 v[78:81], v[52:53], off offset:16
	global_load_dwordx4 v[82:85], v[52:53], off
	global_load_dwordx4 v[86:89], v[52:53], off offset:144
	global_load_dwordx4 v[90:93], v[52:53], off offset:128
	global_load_dwordx4 v[170:173], v[52:53], off offset:272
	global_load_dwordx4 v[174:177], v[52:53], off offset:256
	global_load_dwordx4 v[178:181], v[52:53], off offset:400
	global_load_dwordx4 v[182:185], v[52:53], off offset:384
	s_waitcnt vmcnt(6)
	v_mov_b32_e32 v102, v82
	s_waitcnt vmcnt(4)
	v_mov_b32_e32 v103, v90
	v_mov_b32_e32 v90, v83
	v_pk_mul_f32 v[82:83], v[90:91], v[74:75]
	v_mov_b32_e32 v90, v84
	v_pk_fma_f32 v[82:83], v[102:103], v[62:63], v[82:83]
	v_mov_b32_e32 v91, v92
	v_pk_fma_f32 v[82:83], v[90:91], v[72:73], v[82:83]
	v_mov_b32_e32 v92, v85
	v_pk_fma_f32 v[82:83], v[92:93], v[70:71], v[82:83]
	v_mov_b32_e32 v84, v78
	v_mov_b32_e32 v85, v86
	v_pk_fma_f32 v[82:83], v[84:85], v[60:61], v[82:83]
	v_mov_b32_e32 v86, v79
	v_pk_fma_f32 v[78:79], v[86:87], v[58:59], v[82:83]
	v_mov_b32_e32 v82, v80
	v_mov_b32_e32 v83, v88
	v_pk_fma_f32 v[78:79], v[82:83], v[56:57], v[78:79]
	v_mov_b32_e32 v88, v81
	v_pk_fma_f32 v[78:79], v[88:89], v[54:55], v[78:79]
	s_nop 0
	v_add_f32_e32 v77, 0, v78
	v_add_f32_e32 v77, v77, v79
	s_waitcnt vmcnt(0)
	v_mov_b32_e32 v78, v170
	v_mov_b32_e32 v79, v171
	v_mov_b32_e32 v80, v172
	v_mov_b32_e32 v81, v173
	v_mov_b32_e32 v82, v174
	v_mov_b32_e32 v83, v175
	v_mov_b32_e32 v84, v176
	v_mov_b32_e32 v85, v177
	v_mov_b32_e32 v86, v178
	v_mov_b32_e32 v87, v179
	v_mov_b32_e32 v88, v180
	v_mov_b32_e32 v89, v181
	v_mov_b32_e32 v90, v182
	v_mov_b32_e32 v91, v183
	v_mov_b32_e32 v92, v184
	v_mov_b32_e32 v93, v185
	s_waitcnt vmcnt(2)
	v_mov_b32_e32 v102, v82
	s_waitcnt vmcnt(0)
	v_mov_b32_e32 v103, v90
	v_mov_b32_e32 v90, v83
	v_pk_mul_f32 v[82:83], v[90:91], v[50:51]
	v_mov_b32_e32 v90, v84
	v_pk_fma_f32 v[82:83], v[102:103], v[48:49], v[82:83]
	v_mov_b32_e32 v91, v92
	v_pk_fma_f32 v[82:83], v[90:91], v[46:47], v[82:83]
	v_mov_b32_e32 v92, v85
	v_pk_fma_f32 v[82:83], v[92:93], v[44:45], v[82:83]
	v_mov_b32_e32 v84, v78
	v_mov_b32_e32 v85, v86
	v_pk_fma_f32 v[82:83], v[84:85], v[42:43], v[82:83]
	v_mov_b32_e32 v86, v79
	v_pk_fma_f32 v[78:79], v[86:87], v[40:41], v[82:83]
	v_mov_b32_e32 v82, v80
	v_mov_b32_e32 v83, v88
	v_pk_fma_f32 v[78:79], v[82:83], v[38:39], v[78:79]
	v_mov_b32_e32 v88, v81
	v_pk_fma_f32 v[78:79], v[88:89], v[36:37], v[78:79]
	s_nop 0
	v_add_f32_e32 v77, v77, v78
	v_add_f32_e32 v77, v77, v79
	ds_bpermute_b32 v78, v69, v77
	s_waitcnt lgkmcnt(0)
	v_add_f32_e32 v77, v77, v78
	ds_bpermute_b32 v78, v35, v77
	s_waitcnt lgkmcnt(0)
	v_add_f32_e32 v77, v77, v78
